# mixers: second WG of each CU walks NA then pool/ctx items before its MLA items (rounds 1,2,3,0): pool GEMM items also co-scheduled with the mate's MLA
# speedup vs baseline: 1.0024x; 1.0024x over previous
.LBB0_209:
	v_writelane_b32 v221, s20, 61
	s_movk_i32 s1, 0x800
	s_movk_i32 s0, 0xf600
	s_cmpk_lt_u32 s20, 0xc00
	s_cselect_b32 s1, s1, s0
	s_movk_i32 s0, 0xee00
	s_cmpk_ge_u32 s20, 0x1200
	s_cselect_b32 s1, s0, s1
	s_cmpk_lt_u32 s20, 0x1400
	s_cselect_b32 s1, s1, 0
	s_getreg_b32 s0, hwreg(HW_REG_LDS_ALLOC, 0, 8)
	s_cmp_lg_u32 s0, 0
	s_cselect_b32 s1, s1, 0
	s_add_i32 s20, s20, s1
	s_cmp_ge_i32 s20, s14
	s_mov_b64 s[0:1], -1
	s_cbranch_scc0 .LBB0_211
	s_sub_i32 s0, s20, s14
	s_lshl_b32 s0, s0, 5
	v_mov_b32_e32 v10, v196
	s_and_b32 s2, s0, 0x7fffff80
	s_and_b32 s5, s20, 3
	v_lshrrev_b32_e32 v0, 2, v10
	s_lshl_b64 s[0:1], s[2:3], 10
	v_and_b32_e32 v0, 12, v0
	s_add_u32 s2, s15, s0
	v_lshrrev_b32_e64 v0, v0, s57
	s_addc_u32 s7, s21, s1
	s_lshl_b32 s4, s5, 8
	v_xor_b32_e32 v0, v0, v10
	s_add_u32 s6, s2, s4
	v_ashrrev_i32_e32 v2, 2, v10
	v_lshlrev_b32_e32 v0, 4, v0
	s_addc_u32 s7, s7, 0
	v_and_b32_e32 v0, 48, v0
	v_ashrrev_i32_e32 v3, 31, v2
	v_lshl_add_u64 v[4:5], s[6:7], 0, v[0:1]
	v_lshlrev_b64 v[6:7], 10, v[2:3]
	v_lshl_add_u64 v[70:71], v[4:5], 0, v[6:7]
	v_add_u32_e32 v6, 64, v2
	s_lshl_b32 s2, s5, 15
	v_readlane_b32 s8, v224, 11
	v_ashrrev_i32_e32 v7, 31, v6
	s_add_u32 s8, s8, s2
	v_readlane_b32 s2, v224, 12
	v_lshlrev_b64 v[8:9], 10, v[6:7]
	s_addc_u32 s9, s2, 0
	v_lshl_add_u64 v[72:73], v[4:5], 0, v[8:9]
	v_and_b32_e32 v8, 15, v10
	v_lshlrev_b64 v[4:5], 8, v[6:7]
	v_lshl_add_u32 v12, v10, 4, 0
	v_lshrrev_b32_e32 v6, 1, v10
	s_mov_b32 s2, 0x3ffffc0
	v_lshlrev_b64 v[2:3], 8, v[2:3]
	v_and_or_b32 v13, v6, s2, v8
	v_readfirstlane_b32 s2, v12
	v_add_u32_e32 v8, 0x1000, v12
	v_lshl_add_u64 v[2:3], s[8:9], 0, v[2:3]
	v_and_b32_e32 v6, 12, v10
	s_mov_b32 m0, s2
	v_readfirstlane_b32 s6, v8
	v_lshl_add_u64 v[74:75], v[2:3], 0, v[0:1]
	v_add_u32_e32 v2, 0x2000, v12
	v_lshrrev_b32_e32 v11, 4, v10
	v_lshl_add_u64 v[4:5], s[8:9], 0, v[4:5]
	v_lshrrev_b32_e64 v6, v6, s57
	global_load_lds_dwordx4 v[70:71], off
	s_mov_b32 m0, s6
	v_readfirstlane_b32 s7, v2
	v_add_u32_e32 v2, 0x3000, v12
	v_xor_b32_e32 v6, v6, v11
	global_load_lds_dwordx4 v[72:73], off
	v_lshl_add_u64 v[76:77], v[4:5], 0, v[0:1]
	s_mov_b32 m0, s7
	v_readfirstlane_b32 s8, v2
	v_add_u32_e32 v4, 0x4000, v12
	v_lshlrev_b32_e32 v11, 4, v6
	v_lshlrev_b32_e32 v6, 6, v10
	global_load_lds_dwordx4 v[74:75], off
	s_mov_b32 m0, s8
	v_readfirstlane_b32 s9, v4
	v_and_b32_e32 v10, 0x13c0, v6
	v_lshl_add_u64 v[6:7], v[70:71], 0, 64
	global_load_lds_dwordx4 v[76:77], off
	s_mov_b32 m0, s9
	v_add_u32_e32 v4, 0x5000, v12
	global_load_lds_dwordx4 v[6:7], off
	v_readfirstlane_b32 s9, v4
	v_add_u32_e32 v6, 0x6000, v12
	v_lshl_add_u64 v[8:9], v[72:73], 0, 64
	s_mov_b32 m0, s9
	v_readfirstlane_b32 s9, v6
	v_lshl_add_u64 v[2:3], v[74:75], 0, 64
	global_load_lds_dwordx4 v[8:9], off
	s_mov_b32 m0, s9
	v_and_b32_e32 v0, 48, v11
	global_load_lds_dwordx4 v[2:3], off
	v_add_u32_e32 v2, 0x7000, v12
	v_lshl_add_u64 v[4:5], v[76:77], 0, 64
	v_readfirstlane_b32 s9, v2
	s_mov_b32 m0, s9
	v_add_u32_e32 v11, 0x8000, v12
	global_load_lds_dwordx4 v[4:5], off
	v_add_u32_e32 v14, 0xb000, v12
	v_add_u32_e32 v15, 0xa000, v12
	v_add_u32_e32 v12, 0x9000, v12
	v_readfirstlane_b32 s9, v11
	s_waitcnt vmcnt(4) lgkmcnt(0)
	s_barrier
	v_lshl_add_u64 v[2:3], v[70:71], 0, s[78:79]
	s_mov_b32 m0, s9
	v_readfirstlane_b32 s9, v12
	v_lshl_add_u64 v[4:5], v[72:73], 0, s[78:79]
	global_load_lds_dwordx4 v[2:3], off
	s_mov_b32 m0, s9
	v_readfirstlane_b32 s9, v15
	v_lshl_add_u64 v[8:9], v[74:75], 0, s[78:79]
	global_load_lds_dwordx4 v[4:5], off
	s_mov_b32 m0, s9
	v_readfirstlane_b32 s9, v14
	v_lshl_add_u64 v[6:7], v[76:77], 0, s[78:79]
	global_load_lds_dwordx4 v[8:9], off
	s_mov_b32 m0, s9
	v_add3_u32 v90, 0, v10, v0
	v_lshlrev_b32_e32 v10, 6, v13
	global_load_lds_dwordx4 v[6:7], off
	v_add3_u32 v0, 0, v10, v0
	ds_read_b128 v[2:5], v90 offset:8192
	ds_read_b128 v[6:9], v90 offset:9216
	ds_read_b128 v[10:13], v0
	ds_read_b128 v[14:17], v0 offset:1024
	ds_read_b128 v[22:25], v90 offset:10240
	ds_read_b128 v[30:33], v90 offset:11264
	ds_read_b128 v[50:53], v0 offset:2048
	ds_read_b128 v[54:57], v0 offset:3072
	v_lshl_add_u64 v[70:71], v[70:71], 0, s[84:85]
	s_waitcnt vmcnt(4) lgkmcnt(0)
	s_barrier
	s_mov_b32 m0, s2
	v_lshl_add_u64 v[72:73], v[72:73], 0, s[84:85]
	global_load_lds_dwordx4 v[70:71], off
	s_mov_b32 m0, s6
	v_lshl_add_u64 v[74:75], v[74:75], 0, s[84:85]
	global_load_lds_dwordx4 v[72:73], off
	s_mov_b32 m0, s7
	v_lshl_add_u64 v[76:77], v[76:77], 0, s[84:85]
	global_load_lds_dwordx4 v[74:75], off
	s_mov_b32 m0, s8
	s_waitcnt lgkmcnt(0)
	s_setprio 1
	v_mfma_f32_16x16x32_bf16 v[18:21], v[2:5], v[10:13], 0
	global_load_lds_dwordx4 v[76:77], off
	s_setprio 0
	ds_read_b128 v[70:73], v90 offset:24576
	s_setprio 1
	v_mfma_f32_16x16x32_bf16 v[26:29], v[6:9], v[10:13], 0
	s_lshl_b32 s2, s5, 9
	v_lshl_add_u64 v[94:95], v[146:147], 0, s[2:3]
	v_readlane_b32 s2, v224, 1
	v_mfma_f32_16x16x32_bf16 v[34:37], v[22:25], v[10:13], 0
	s_add_u32 s0, s2, s0
	v_readlane_b32 s2, v224, 2
	s_addc_u32 s1, s2, s1
	v_mfma_f32_16x16x32_bf16 v[10:13], v[30:33], v[10:13], 0
	s_mov_b32 s2, 0xfffffc0
	s_add_u32 s0, s0, s4
	s_addc_u32 s1, s1, 0
	v_mfma_f32_16x16x32_bf16 v[38:41], v[2:5], v[14:17], 0
	v_mfma_f32_16x16x32_bf16 v[42:45], v[6:9], v[14:17], 0
	v_mfma_f32_16x16x32_bf16 v[46:49], v[22:25], v[14:17], 0
	v_mfma_f32_16x16x32_bf16 v[14:17], v[30:33], v[14:17], 0
	v_mfma_f32_16x16x32_bf16 v[58:61], v[2:5], v[50:53], 0
	v_mfma_f32_16x16x32_bf16 v[62:65], v[6:9], v[50:53], 0
	v_mfma_f32_16x16x32_bf16 v[66:69], v[22:25], v[50:53], 0
	v_mfma_f32_16x16x32_bf16 v[50:53], v[30:33], v[50:53], 0
	v_mfma_f32_16x16x32_bf16 v[2:5], v[2:5], v[54:57], 0
	v_mfma_f32_16x16x32_bf16 v[6:9], v[6:9], v[54:57], 0
	v_mfma_f32_16x16x32_bf16 v[22:25], v[22:25], v[54:57], 0
	v_mfma_f32_16x16x32_bf16 v[30:33], v[30:33], v[54:57], 0
	s_setprio 0
	ds_read_b128 v[54:57], v90 offset:25600
	ds_read_b128 v[74:77], v0 offset:16384
	ds_read_b128 v[78:81], v0 offset:17408
	ds_read_b128 v[82:85], v90 offset:26624
	ds_read_b128 v[86:89], v90 offset:27648
	s_waitcnt lgkmcnt(0)
	s_setprio 1
	v_mfma_f32_16x16x32_bf16 v[18:21], v[70:73], v[74:77], v[18:21]
	v_mfma_f32_16x16x32_bf16 v[26:29], v[54:57], v[74:77], v[26:29]
	v_mfma_f32_16x16x32_bf16 v[34:37], v[82:85], v[74:77], v[34:37]
	v_mfma_f32_16x16x32_bf16 v[10:13], v[86:89], v[74:77], v[10:13]
	v_mfma_f32_16x16x32_bf16 v[38:41], v[70:73], v[78:81], v[38:41]
	v_mfma_f32_16x16x32_bf16 v[42:45], v[54:57], v[78:81], v[42:45]
	v_mfma_f32_16x16x32_bf16 v[46:49], v[82:85], v[78:81], v[46:49]
	v_mfma_f32_16x16x32_bf16 v[14:17], v[86:89], v[78:81], v[14:17]
	s_setprio 0
	ds_read_b128 v[74:77], v0 offset:18432
	ds_read_b128 v[78:81], v0 offset:19456
	s_waitcnt vmcnt(4) lgkmcnt(0)
	s_barrier
	s_waitcnt lgkmcnt(0)
	s_setprio 1
	v_mfma_f32_16x16x32_bf16 v[58:61], v[70:73], v[74:77], v[58:61]
	v_mfma_f32_16x16x32_bf16 v[62:65], v[54:57], v[74:77], v[62:65]
	v_mfma_f32_16x16x32_bf16 v[66:69], v[82:85], v[74:77], v[66:69]
	v_mfma_f32_16x16x32_bf16 v[50:53], v[86:89], v[74:77], v[50:53]
	v_mfma_f32_16x16x32_bf16 v[2:5], v[70:73], v[78:81], v[2:5]
	v_mfma_f32_16x16x32_bf16 v[6:9], v[54:57], v[78:81], v[6:9]
	s_setprio 0
	ds_read_b128 v[54:57], v90 offset:40960
	s_setprio 1
	v_mfma_f32_16x16x32_bf16 v[22:25], v[82:85], v[78:81], v[22:25]
	v_mfma_f32_16x16x32_bf16 v[30:33], v[86:89], v[78:81], v[30:33]
	s_setprio 0
	ds_read_b128 v[70:73], v90 offset:41984
	ds_read_b128 v[74:77], v0 offset:32768
	ds_read_b128 v[78:81], v0 offset:33792
	ds_read_b128 v[82:85], v90 offset:43008
	ds_read_b128 v[86:89], v90 offset:44032
	s_waitcnt lgkmcnt(0)
	s_setprio 1
	v_mfma_f32_16x16x32_bf16 v[18:21], v[54:57], v[74:77], v[18:21]
	v_mfma_f32_16x16x32_bf16 v[26:29], v[70:73], v[74:77], v[26:29]
	v_mfma_f32_16x16x32_bf16 v[34:37], v[82:85], v[74:77], v[34:37]
	v_mfma_f32_16x16x32_bf16 v[10:13], v[86:89], v[74:77], v[10:13]
	v_mfma_f32_16x16x32_bf16 v[38:41], v[54:57], v[78:81], v[38:41]
	v_mfma_f32_16x16x32_bf16 v[42:45], v[70:73], v[78:81], v[42:45]
	v_mfma_f32_16x16x32_bf16 v[46:49], v[82:85], v[78:81], v[46:49]
	v_mfma_f32_16x16x32_bf16 v[14:17], v[86:89], v[78:81], v[14:17]
	s_setprio 0
	ds_read_b128 v[74:77], v0 offset:34816
	ds_read_b128 v[78:81], v0 offset:35840
	s_waitcnt vmcnt(0) lgkmcnt(0)
	s_barrier
	s_waitcnt lgkmcnt(0)
	s_setprio 1
	v_mfma_f32_16x16x32_bf16 v[58:61], v[54:57], v[74:77], v[58:61]
	v_mfma_f32_16x16x32_bf16 v[62:65], v[70:73], v[74:77], v[62:65]
	v_mfma_f32_16x16x32_bf16 v[66:69], v[82:85], v[74:77], v[66:69]
	v_mfma_f32_16x16x32_bf16 v[50:53], v[86:89], v[74:77], v[50:53]
	v_mfma_f32_16x16x32_bf16 v[2:5], v[54:57], v[78:81], v[2:5]
	s_setprio 0
	ds_read_b128 v[54:57], v90 offset:8192
	s_setprio 1
	v_mfma_f32_16x16x32_bf16 v[6:9], v[70:73], v[78:81], v[6:9]
	v_mfma_f32_16x16x32_bf16 v[22:25], v[82:85], v[78:81], v[22:25]
	v_mfma_f32_16x16x32_bf16 v[30:33], v[86:89], v[78:81], v[30:33]
	s_setprio 0
	ds_read_b128 v[70:73], v90 offset:9216
	ds_read_b128 v[74:77], v0
	ds_read_b128 v[78:81], v0 offset:1024
	ds_read_b128 v[82:85], v90 offset:10240
	ds_read_b128 v[86:89], v90 offset:11264
	s_waitcnt lgkmcnt(0)
	s_setprio 1
	v_mfma_f32_16x16x32_bf16 v[18:21], v[54:57], v[74:77], v[18:21]
	v_mfma_f32_16x16x32_bf16 v[26:29], v[70:73], v[74:77], v[26:29]
	v_mfma_f32_16x16x32_bf16 v[34:37], v[82:85], v[74:77], v[34:37]
	v_mfma_f32_16x16x32_bf16 v[10:13], v[86:89], v[74:77], v[10:13]
	v_mfma_f32_16x16x32_bf16 v[38:41], v[54:57], v[78:81], v[38:41]
	v_mfma_f32_16x16x32_bf16 v[42:45], v[70:73], v[78:81], v[42:45]
	v_mfma_f32_16x16x32_bf16 v[46:49], v[82:85], v[78:81], v[46:49]
	v_mfma_f32_16x16x32_bf16 v[14:17], v[86:89], v[78:81], v[14:17]
	s_setprio 0
	ds_read_b128 v[74:77], v0 offset:2048
	ds_read_b128 v[78:81], v0 offset:3072
	s_waitcnt vmcnt(0) lgkmcnt(0)
	s_barrier
	s_setprio 1
	v_mfma_f32_16x16x32_bf16 v[58:61], v[54:57], v[74:77], v[58:61]
	global_load_dwordx4 v[90:93], v[94:95], off
	v_mfma_f32_16x16x32_bf16 v[2:5], v[54:57], v[78:81], v[2:5]
	global_load_dwordx4 v[54:57], v[94:95], off offset:128
	v_mfma_f32_16x16x32_bf16 v[62:65], v[70:73], v[74:77], v[62:65]
	v_mfma_f32_16x16x32_bf16 v[66:69], v[82:85], v[74:77], v[66:69]
	v_mfma_f32_16x16x32_bf16 v[50:53], v[86:89], v[74:77], v[50:53]
	global_load_dwordx4 v[74:77], v[94:95], off offset:64
	s_setprio 0
	s_waitcnt vmcnt(2)
	v_pk_mul_f32 v[18:19], v[18:19], v[90:91]
	s_setprio 1
	v_mfma_f32_16x16x32_bf16 v[6:9], v[70:73], v[78:81], v[6:9]
	global_load_dwordx4 v[70:73], v[94:95], off offset:192
	s_setprio 0
	s_waitcnt vmcnt(2)
	v_pk_mul_f32 v[34:35], v[34:35], v[54:55]
	v_pk_mul_f32 v[46:47], v[46:47], v[54:55]
	s_setprio 1
	v_mfma_f32_16x16x32_bf16 v[22:25], v[82:85], v[78:81], v[22:25]
	v_mul_f32_e64 v66, v66, v54
	v_mul_f32_e64 v67, v67, v55
	v_pk_mul_f32 v[36:37], v[36:37], v[56:57]
	v_pk_mul_f32 v[48:49], v[48:49], v[56:57]
	v_mfma_f32_16x16x32_bf16 v[30:33], v[86:89], v[78:81], v[30:33]
	v_mul_f32_e64 v20, v20, v92
	v_mul_f32_e64 v21, v21, v93
	s_nop 0
	v_pk_mul_f32 v[22:23], v[22:23], v[54:55]
	v_pk_mul_f32 v[54:55], v[68:69], v[56:57]
	v_pk_mul_f32 v[24:25], v[24:25], v[56:57]
	v_mov_b32_e32 v56, v196
	s_setprio 0
	s_waitcnt vmcnt(1)
	v_pk_mul_f32 v[26:27], v[26:27], v[74:75]
	v_and_b32_e32 v57, 15, v56
	v_lshrrev_b32_e32 v68, 1, v56
	v_and_b32_e32 v0, 64, v56
	v_and_or_b32 v69, v68, s2, v57
	v_pk_mul_f32 v[28:29], v[28:29], v[76:77]
	v_lshl_add_u32 v0, v0, 1, 0
	v_and_b32_e32 v68, 24, v68
	v_mul_lo_u32 v69, v69, s30
	v_add3_u32 v0, v0, v68, v69
	v_cvt_pk_bf16_f32 v18, v18, v19
	v_cvt_pk_bf16_f32 v19, v20, v21
	v_cvt_pk_bf16_f32 v20, v26, v27
	v_cvt_pk_bf16_f32 v21, v28, v29
	v_pk_mul_f32 v[38:39], v[38:39], v[90:91]
	v_pk_mul_f32 v[40:41], v[40:41], v[92:93]
	v_pk_mul_f32 v[42:43], v[42:43], v[74:75]
	v_pk_mul_f32 v[44:45], v[44:45], v[76:77]
	ds_write2_b64 v0, v[18:19], v[20:21] offset1:4
	v_cvt_pk_bf16_f32 v18, v34, v35
	v_cvt_pk_bf16_f32 v19, v36, v37
	v_pk_mul_f32 v[2:3], v[2:3], v[90:91]
	v_pk_mul_f32 v[4:5], v[4:5], v[92:93]
	v_pk_mul_f32 v[6:7], v[6:7], v[74:75]
	v_pk_mul_f32 v[8:9], v[8:9], v[76:77]
	v_pk_mul_f32 v[58:59], v[58:59], v[90:91]
	v_pk_mul_f32 v[60:61], v[60:61], v[92:93]
	v_pk_mul_f32 v[62:63], v[62:63], v[74:75]
	v_pk_mul_f32 v[64:65], v[64:65], v[76:77]
	v_cvt_pk_bf16_f32 v2, v2, v3
	v_cvt_pk_bf16_f32 v3, v4, v5
	v_cvt_pk_bf16_f32 v4, v6, v7
	v_cvt_pk_bf16_f32 v5, v8, v9
	v_add_u32_e32 v6, 0x100, v56
	s_waitcnt vmcnt(0)
	v_pk_mul_f32 v[10:11], v[10:11], v[70:71]
	v_pk_mul_f32 v[12:13], v[12:13], v[72:73]
	v_cvt_pk_bf16_f32 v10, v10, v11
	v_cvt_pk_bf16_f32 v11, v12, v13
	v_pk_mul_f32 v[14:15], v[14:15], v[70:71]
	v_pk_mul_f32 v[16:17], v[16:17], v[72:73]
	ds_write2_b64 v0, v[18:19], v[10:11] offset0:8 offset1:12
	v_cvt_pk_bf16_f32 v10, v38, v39
	v_cvt_pk_bf16_f32 v11, v40, v41
	v_cvt_pk_bf16_f32 v12, v42, v43
	v_cvt_pk_bf16_f32 v13, v44, v45
	v_add_u32_e32 v18, 0x1000, v0
	v_pk_mul_f32 v[30:31], v[30:31], v[70:71]
	v_pk_mul_f32 v[32:33], v[32:33], v[72:73]
	ds_write2_b64 v18, v[10:11], v[12:13] offset0:32 offset1:36
	v_cvt_pk_bf16_f32 v10, v46, v47
	v_cvt_pk_bf16_f32 v11, v48, v49
	v_cvt_pk_bf16_f32 v12, v14, v15
	v_cvt_pk_bf16_f32 v13, v16, v17
	v_add_u32_e32 v14, 0x2000, v0
	v_add_u32_e32 v0, 0x3000, v0
	v_pk_mul_f32 v[50:51], v[50:51], v[70:71]
	v_pk_mul_f32 v[52:53], v[52:53], v[72:73]
	ds_write2_b64 v18, v[10:11], v[12:13] offset0:40 offset1:44
	v_cvt_pk_bf16_f32 v10, v58, v59
	v_cvt_pk_bf16_f32 v11, v60, v61
	v_cvt_pk_bf16_f32 v12, v62, v63
	v_cvt_pk_bf16_f32 v13, v64, v65
	ds_write2_b64 v0, v[2:3], v[4:5] offset0:96 offset1:100
	v_cvt_pk_bf16_f32 v2, v22, v23
	v_cvt_pk_bf16_f32 v3, v24, v25
	v_cvt_pk_bf16_f32 v4, v30, v31
	v_cvt_pk_bf16_f32 v5, v32, v33
	ds_write2_b64 v14, v[10:11], v[12:13] offset0:64 offset1:68
	v_cvt_pk_bf16_f32 v10, v66, v67
	v_cvt_pk_bf16_f32 v11, v54, v55
	v_cvt_pk_bf16_f32 v12, v50, v51
	v_cvt_pk_bf16_f32 v13, v52, v53
	ds_write2_b64 v0, v[2:3], v[4:5] offset0:104 offset1:108
	v_lshlrev_b32_e32 v0, 4, v57
	v_ashrrev_i32_e32 v2, 4, v56
	ds_write2_b64 v14, v[10:11], v[12:13] offset0:72 offset1:76
	v_lshl_add_u64 v[10:11], s[0:1], 0, v[0:1]
	v_add_u32_e32 v0, 0, v0
	v_ashrrev_i32_e32 v3, 31, v2
	v_mad_u64_u32 v[4:5], s[0:1], v2, s30, v[0:1]
	v_lshlrev_b64 v[2:3], 10, v[2:3]
	s_waitcnt lgkmcnt(0)
	s_barrier
	v_lshl_add_u64 v[12:13], v[10:11], 0, v[2:3]
	ds_read_b128 v[2:5], v4
	v_ashrrev_i32_e32 v14, 4, v6
	v_mad_u64_u32 v[6:7], s[0:1], v14, s30, v[0:1]
	ds_read_b128 v[6:9], v6
	v_ashrrev_i32_e32 v15, 31, v14
	s_waitcnt lgkmcnt(1)
	global_store_dwordx4 v[12:13], v[2:5], off
	s_nop 1
	v_lshlrev_b64 v[2:3], 10, v[14:15]
	v_lshl_add_u64 v[2:3], v[10:11], 0, v[2:3]
	s_waitcnt lgkmcnt(0)
	global_store_dwordx4 v[2:3], v[6:9], off
	v_add_u32_e32 v2, 0x200, v56
	v_ashrrev_i32_e32 v2, 4, v2
	v_ashrrev_i32_e32 v3, 31, v2
	v_mad_u64_u32 v[4:5], s[0:1], v2, s30, v[0:1]
	v_lshlrev_b64 v[2:3], 10, v[2:3]
	v_add_u32_e32 v6, 0x300, v56
	v_lshl_add_u64 v[12:13], v[10:11], 0, v[2:3]
	ds_read_b128 v[2:5], v4
	v_ashrrev_i32_e32 v14, 4, v6
	v_mad_u64_u32 v[6:7], s[0:1], v14, s30, v[0:1]
	ds_read_b128 v[6:9], v6
	v_ashrrev_i32_e32 v15, 31, v14
	s_waitcnt lgkmcnt(1)
	global_store_dwordx4 v[12:13], v[2:5], off
	s_nop 1
	v_lshlrev_b64 v[2:3], 10, v[14:15]
	v_lshl_add_u64 v[2:3], v[10:11], 0, v[2:3]
	s_waitcnt lgkmcnt(0)
	global_store_dwordx4 v[2:3], v[6:9], off
	v_add_u32_e32 v2, 0x400, v56
	v_ashrrev_i32_e32 v2, 4, v2
	v_ashrrev_i32_e32 v3, 31, v2
	v_mad_u64_u32 v[4:5], s[0:1], v2, s30, v[0:1]
	v_lshlrev_b64 v[2:3], 10, v[2:3]
	v_add_u32_e32 v6, 0x500, v56
	v_lshl_add_u64 v[12:13], v[10:11], 0, v[2:3]
	ds_read_b128 v[2:5], v4
	v_ashrrev_i32_e32 v14, 4, v6
	v_mad_u64_u32 v[6:7], s[0:1], v14, s30, v[0:1]
	ds_read_b128 v[6:9], v6
	v_ashrrev_i32_e32 v15, 31, v14
	s_waitcnt lgkmcnt(1)
	global_store_dwordx4 v[12:13], v[2:5], off
	s_nop 1
	v_lshlrev_b64 v[2:3], 10, v[14:15]
	v_lshl_add_u64 v[2:3], v[10:11], 0, v[2:3]
	s_waitcnt lgkmcnt(0)
	global_store_dwordx4 v[2:3], v[6:9], off
	v_add_u32_e32 v2, 0x600, v56
	v_ashrrev_i32_e32 v2, 4, v2
	v_ashrrev_i32_e32 v3, 31, v2
	v_mad_u64_u32 v[4:5], s[0:1], v2, s30, v[0:1]
	v_lshlrev_b64 v[2:3], 10, v[2:3]
	v_add_u32_e32 v6, 0x700, v56
	v_lshl_add_u64 v[12:13], v[10:11], 0, v[2:3]
	ds_read_b128 v[2:5], v4
	v_ashrrev_i32_e32 v14, 4, v6
	v_mad_u64_u32 v[6:7], s[0:1], v14, s30, v[0:1]
	ds_read_b128 v[6:9], v6
	v_ashrrev_i32_e32 v15, 31, v14
	s_waitcnt lgkmcnt(1)
	global_store_dwordx4 v[12:13], v[2:5], off
	s_mov_b64 s[0:1], 0
	s_nop 0
	v_lshlrev_b64 v[2:3], 10, v[14:15]
	v_lshl_add_u64 v[2:3], v[10:11], 0, v[2:3]
	s_waitcnt lgkmcnt(0)
	global_store_dwordx4 v[2:3], v[6:9], off
	s_barrier
